# prep phase: half the workgroups (wg bit 3) compute the S5 derived matrices before the streaming conversions instead of after (same work, overlaps latency-bound and bandwidth-bound parts)
# speedup vs baseline: 1.0641x; 1.0011x over previous
.LBB0_17:
	s_mov_b64 s[100:101], s[0:1]
	s_mov_b32 s98, 0
	s_load_dwordx16 s[16:31], s[0:1], 0x40
	s_cmp_lt_i32 s74, 1
	s_cselect_b64 s[78:79], -1, 0
	s_cmp_gt_i32 s75, 0
	s_cselect_b64 s[6:7], -1, 0
	s_and_b64 s[6:7], s[78:79], s[6:7]
	s_andn2_b64 vcc, exec, s[6:7]
	s_cbranch_vccnz .LBB0_280
	s_bitcmp1_b32 s2, 3
	s_cbranch_scc0 .Lpr_s1
	s_mov_b32 s98, 1
	s_load_dwordx8 s[44:51], s[0:1], 0x20
	v_and_b32_e32 v25, 63, v192
	v_and_b32_e32 v24, 31, v192
	s_waitcnt lgkmcnt(0)
	s_ashr_i32 s3, s2, 31
	s_lshl_b64 s[0:1], s[2:3], 9
	v_mov_b32_e32 v193, 0
	s_nop 1
	v_lshl_add_u64 v[16:17], s[0:1], 0, v[192:193]
	s_ashr_i32 s13, s34, 31
	s_mov_b32 s12, s34
	s_lshl_b64 s[24:25], s[12:13], 9
	v_lshlrev_b32_e32 v18, 3, v192
	v_lshlrev_b32_e32 v4, 2, v192
	s_mov_b64 s[0:1], 0
	s_branch .LBB0_209
.Lpr_s1:
	s_load_dwordx16 s[36:51], s[0:1], 0x0
	v_lshrrev_b32_e32 v0, 6, v192
	v_writelane_b32 v242, s90, 0
	v_lshl_add_u32 v5, s2, 3, v0
	s_movk_i32 s3, 0x2c00
	v_writelane_b32 v242, s88, 1
	v_and_b32_e32 v25, 63, v192
	v_cmp_gt_i32_e32 vcc, s3, v5
	v_and_b32_e32 v24, 31, v192
	v_lshlrev_b32_e32 v26, 1, v5
	v_writelane_b32 v242, s89, 2
	s_and_saveexec_b64 s[8:9], vcc
	s_cbranch_execz .LBB0_185
	s_load_dwordx16 s[52:67], s[0:1], 0x80
	s_lshl_b32 s3, s34, 3
	s_movk_i32 s0, 0x2100
	v_mad_u32_u24 v1, v0, s0, 0
	s_add_u32 s0, s72, 0x2b80000
	s_addc_u32 s1, s73, 0
	v_writelane_b32 v242, s0, 3
	v_lshrrev_b32_e32 v0, 5, v25
	v_mov_b32_e32 v2, 0x108
	v_writelane_b32 v242, s1, 4
	s_movk_i32 s0, 0x84
	v_mad_u32_u24 v33, v0, s0, v2
	v_mov_b32_e32 v2, 0x210
	v_mad_u32_u24 v34, v0, s0, v2
	v_mov_b32_e32 v2, 0x420
	v_mad_u32_u24 v35, v0, s0, v2
	v_mov_b32_e32 v2, 0x630
	v_mad_u32_u24 v36, v0, s0, v2
	v_mov_b32_e32 v2, 0x840
	v_mad_u32_u24 v37, v0, s0, v2
	v_mov_b32_e32 v2, 0xa50
	v_mad_u32_u24 v38, v0, s0, v2
	v_mov_b32_e32 v2, 0xc60
	v_mad_u32_u24 v39, v0, s0, v2
	v_mov_b32_e32 v2, 0xe70
	v_mad_u32_u24 v40, v0, s0, v2
	v_mov_b32_e32 v2, 0x1080
	v_mad_u32_u24 v41, v0, s0, v2
	v_mov_b32_e32 v2, 0x1290
	v_mad_u32_u24 v42, v0, s0, v2
	v_mov_b32_e32 v2, 0x14a0
	v_lshlrev_b32_e32 v16, 2, v24
	v_mad_u32_u24 v43, v0, s0, v2
	v_mov_b32_e32 v2, 0x16b0
	v_add_u32_e32 v27, v1, v16
	v_mad_u32_u24 v44, v0, s0, v2
	v_mov_b32_e32 v2, 0x18c0
	v_mad_u32_u24 v32, v0, s0, v27
	v_mad_u32_u24 v45, v0, s0, v2
	s_add_u32 s0, s72, 0x2a80000
	s_addc_u32 s1, s73, 0
	v_writelane_b32 v242, s0, 5
	v_lshlrev_b32_e32 v2, 3, v192
	v_lshrrev_b32_e32 v46, 3, v25
	v_writelane_b32 v242, s1, 6
	s_add_u32 s0, s72, 0x2680000
	s_addc_u32 s1, s73, 0
	v_and_b32_e32 v4, 56, v2
	s_add_u32 s82, s72, 0x1680000
	v_mul_u32_u24_e32 v2, 0x84, v4
	v_lshlrev_b32_e32 v6, 2, v46
	s_addc_u32 s83, s73, 0
	v_mov_b32_e32 v3, 0
	v_add3_u32 v47, v1, v2, v6
	v_writelane_b32 v242, s0, 7
	s_add_u32 s84, s72, 0x680000
	v_lshlrev_b32_e32 v2, 1, v4
	v_writelane_b32 v242, s1, 8
	s_addc_u32 s85, s73, 0
	v_lshl_add_u64 v[6:7], s[72:73], 0, v[2:3]
	s_mov_b64 s[0:1], 0x480000
	v_lshl_add_u64 v[8:9], v[6:7], 0, s[0:1]
	s_mov_b64 s[0:1], 0x400000
	s_waitcnt lgkmcnt(0)
	s_cmp_lg_u64 s[52:53], 0
	v_lshl_add_u64 v[10:11], v[6:7], 0, s[0:1]
	s_cselect_b64 s[0:1], -1, 0
	v_writelane_b32 v242, s0, 9
	s_cmp_lg_u64 s[56:57], 0
	v_mov_b32_e32 v17, v3
	v_writelane_b32 v242, s1, 10
	s_cselect_b64 s[0:1], -1, 0
	v_writelane_b32 v242, s0, 11
	s_cmp_lg_u64 s[64:65], 0
	v_or_b32_e32 v48, 8, v46
	v_writelane_b32 v242, s1, 12
	s_cselect_b64 s[0:1], -1, 0
	s_cmp_lg_u64 s[58:59], 0
	s_cselect_b64 s[86:87], -1, 0
	s_cmp_lg_u64 s[40:41], 0
	v_or_b32_e32 v49, 16, v46
	v_or_b32_e32 v50, 24, v46
	v_lshl_add_u64 v[12:13], s[30:31], 0, v[16:17]
	v_lshl_add_u64 v[14:15], s[24:25], 0, v[16:17]
	v_lshl_add_u64 v[16:17], s[42:43], 0, v[16:17]
	v_writelane_b32 v242, s0, 13
	v_mov_b32_e32 v1, v3
	v_lshlrev_b32_e32 v51, 5, v5
	v_lshlrev_b32_e32 v52, 7, v5
	v_lshlrev_b32_e32 v53, 3, v5
	v_lshlrev_b32_e32 v54, 1, v5
	v_lshlrev_b32_e32 v55, 2, v5
	v_lshlrev_b32_e32 v18, 2, v24
	v_mov_b32_e32 v56, v5
	s_cselect_b64 s[88:89], -1, 0
	s_lshl_b32 s12, s34, 8
	s_lshl_b32 s13, s34, 10
	s_lshl_b32 s14, s34, 6
	s_lshl_b32 s15, s34, 4
	s_lshl_b32 s80, s34, 5
	s_movk_i32 s81, 0x200
	s_mov_b64 s[90:91], 0
	v_writelane_b32 v242, s1, 14
	s_branch .LBB0_22

.LBB0_209:
	s_or_b64 exec, exec, s[0:1]
	s_cmp_eq_u32 s98, 2
	s_cbranch_scc1 .LBB0_280
	s_mov_b64 s[0:1], 0x800
	v_cmp_gt_u64_e32 vcc, s[0:1], v[16:17]
	s_and_saveexec_b64 s[14:15], vcc
	s_cbranch_execz .LBB0_216
	v_mov_b32_e32 v1, 0
	s_lshl_b64 s[0:1], s[2:3], 11
	v_mov_b32_e32 v5, v1
	v_lshl_add_u64 v[2:3], s[0:1], 0, v[4:5]
	s_lshl_b64 s[30:31], s[12:13], 11
	s_lshl_b64 s[0:1], s[2:3], 12
	s_add_u32 s0, s72, s0
	v_mov_b32_e32 v19, v1
	s_addc_u32 s1, s73, s1
	v_lshl_add_u64 v[6:7], s[0:1], 0, v[18:19]
	s_mov_b64 s[0:1], 0x4800000
	v_lshl_add_u64 v[6:7], v[6:7], 0, s[0:1]
	s_lshl_b64 s[36:37], s[12:13], 12
	s_mov_b64 s[38:39], 0
	s_brev_b32 s52, 18
	s_mov_b32 s53, 0xfe5163ab
	s_mov_b32 s54, 0x3c439041
	s_mov_b32 s55, 0xdb629599
	s_mov_b32 s56, 0xf534ddc0
	s_mov_b32 s57, 0xfc2757d1
	s_mov_b32 s58, 0x4e441529
	s_mov_b32 s59, 0xa2f9836e
	s_mov_b32 s60, 0x3fc90fda
	s_mov_b32 s61, 0x3f22f983
	s_mov_b32 s62, 0xbfc90fda
	v_mov_b32_e32 v5, 0x3c0881c4
	v_mov_b32_e32 v10, 0xbab64f3b
	s_brev_b32 s63, 1
	s_movk_i32 s64, 0x1f8
	s_mov_b64 s[40:41], 0x7ff
	v_not_b32_e32 v11, 63
	v_not_b32_e32 v12, 31
	v_mov_b32_e32 v13, 0x7fc00000
	v_mov_b64_e32 v[8:9], v[16:17]
	s_branch .LBB0_212

.LBB0_280:
	s_cmp_eq_u32 s98, 1
	s_cbranch_scc0 .Lpr_done
	s_mov_b32 s98, 2
	s_mov_b64 s[0:1], s[100:101]
	s_load_dwordx16 s[16:31], s[100:101], 0x40
	s_load_dwordx2 s[68:69], s[100:101], 0xc0
	s_waitcnt lgkmcnt(0)
	s_branch .Lpr_s1
